# v28 + at the barrier after attention the first-arriving block of each XCD issues an early L2 write-back
# baseline (speedup 1.0000x reference)
; __device__ __forceinline__ unsigned xb_ld(unsigned* p)              { return __hip_atomic_load(p, __ATOMIC_RELAXED, __HIP_MEMORY_SCOPE_AGENT); }
; __device__ __forceinline__ unsigned xb_add(unsigned* p, unsigned v) { return __hip_atomic_fetch_add(p, v, __ATOMIC_RELAXED, __HIP_MEMORY_SCOPE_AGENT); }
; #define XB_SPIN(cond, bar) do { unsigned _sp = 0; while (cond) { __builtin_amdgcn_s_sleep(1); \
;     if ((++_sp & 255u) == 0u) { if (xb_ld(&(bar)[XB_TMO])) break; if (_sp > XB_SPIN_CAP) { atomicAdd(&(bar)[XB_TMO], 1u); break; } } } } while (0)
; __device__ __forceinline__ void xcd_barrier(const XcdBarrier& b) {
;     ...
;         const unsigned old = xb_add(&bar[XB_XSUB(b.x)], 1u);
;         const unsigned gen = old / nloc;
;         if (old + 1u == (gen + 1u) * nloc) {
;             __builtin_amdgcn_fence(__ATOMIC_RELEASE, "agent");
;             asm volatile("s_waitcnt vmcnt(0)" ::: "memory");
;             const unsigned og = xb_add(&bar[XB_TOP], 1u);
;             const unsigned tg = og / nx;
;             if (og + 1u == (tg + 1u) * nx) xb_add(&bar[XB_TOPGEN], 1u);
;             else XB_SPIN(xb_ld(&bar[XB_TOPGEN]) == tg, bar);
;             __builtin_amdgcn_fence(__ATOMIC_ACQUIRE, "agent");
;             xb_add(&bar[XB_XGEN(b.x)], 1u);
;             asm volatile("s_waitcnt vmcnt(0)" ::: "memory");
;         } else {
;             XB_SPIN(xb_ld(&bar[XB_XGEN(b.x)]) == gen, bar);
;             __builtin_amdgcn_fence(__ATOMIC_ACQUIRE, "agent");
;             asm volatile("s_waitcnt vmcnt(0)" ::: "memory");
;         }
.LBB0_397:
	s_or_b64 exec, exec, s[22:23]
	v_cvt_f32_u32_e32 v4, v2
	s_waitcnt vmcnt(0)
	v_readfirstlane_b32 s8, v3
	v_sub_u32_e32 v3, 0, v2
	v_rcp_iflag_f32_e32 v4, v4
	v_add_u32_e32 v5, s8, v1
	v_mul_f32_e32 v4, 0x4f7ffffe, v4
	v_cvt_u32_f32_e32 v4, v4
	v_mul_lo_u32 v1, v3, v4
	v_mul_hi_u32 v1, v4, v1
	v_add_u32_e32 v1, v4, v1
	v_mul_hi_u32 v1, v5, v1
	v_mul_lo_u32 v3, v1, v2
	v_sub_u32_e32 v3, v5, v3
	v_add_u32_e32 v4, 1, v1
	v_cmp_ge_u32_e32 vcc, v3, v2
	s_nop 1
	v_cndmask_b32_e32 v1, v1, v4, vcc
	v_sub_u32_e32 v4, v3, v2
	v_cndmask_b32_e32 v3, v3, v4, vcc
	v_add_u32_e32 v4, 1, v1
	v_cmp_ge_u32_e32 vcc, v3, v2
	v_add_u32_e32 v3, 1, v5
	s_nop 0
	v_cndmask_b32_e32 v1, v1, v4, vcc
	v_mul_lo_u32 v4, v2, v1
	v_add_u32_e32 v2, v4, v2
	v_cmp_ne_u32_e32 vcc, v3, v2
	s_and_saveexec_b64 s[8:9], vcc
	s_xor_b64 s[8:9], exec, s[8:9]
	s_cbranch_execz .LBB0_411
	s_waitcnt lgkmcnt(0)
	v_cmp_eq_u32_e32 vcc, v5, v4
	s_and_saveexec_b64 s[96:97], vcc
	s_cbranch_execz .Learlywb_skip
	buffer_wbl2 sc1
	s_waitcnt vmcnt(0)
.Learlywb_skip:
	s_or_b64 exec, exec, s[96:97]
	v_mov_b32_e32 v0, 0x2000
	global_load_dword v0, v0, s[4:5] offset:1024 sc1
	s_add_u32 s38, s4, 0x2400
	s_addc_u32 s39, s5, 0
	s_waitcnt vmcnt(0)
	v_cmp_eq_u32_e32 vcc, v0, v1
	s_and_saveexec_b64 s[22:23], vcc
	s_cbranch_execz .LBB0_410
	s_add_u32 s24, s30, 0x20200
	s_addc_u32 s25, s31, 0
	s_mov_b32 s54, 1
	s_mov_b64 s[42:43], 0
	v_mov_b32_e32 v0, 0
	s_branch .LBB0_401
